# grid barrier: returning arrival atomic, last arriver releases 8 sharded flag words, pollers poll own shard (s_sleep 8)
# speedup vs baseline: 1.0458x; 1.0458x over previous
.LBB0_16:
	s_waitcnt vmcnt(0) lgkmcnt(0)
	s_barrier
	s_mov_b64 s[0:1], exec
	v_readlane_b32 s2, v252, 33
	v_readlane_b32 s3, v252, 34
	s_and_b64 s[2:3], s[0:1], s[2:3]
	s_mov_b64 exec, s[2:3]
	s_cbranch_execz .LBB0_22
	buffer_wbl2 sc1
	s_waitcnt vmcnt(0)
	v_readlane_b32 s4, v250, 8
	v_readlane_b32 s5, v250, 9
	v_mov_b32_e32 v0, 1
	s_load_dword s2, s[84:85], 0x0
	s_nop 4
	global_atomic_add v1, v145, v0, s[4:5] sc0
	v_readlane_b32 s3, v255, 40
	s_waitcnt lgkmcnt(0)
	s_mul_i32 s2, s2, s12
	s_nop 3
	s_and_b32 s3, s3, 7
	s_lshl_b32 s3, s3, 6
	v_mov_b32_e32 v2, s3
	s_waitcnt vmcnt(0)
	s_nop 0
	v_readfirstlane_b32 s3, v1
	s_nop 3
	s_add_u32 s3, s3, 1
	s_cmp_lg_u32 s3, s2
	s_cbranch_scc1 .Lgb_poll
	global_atomic_add v145, v0, s[4:5] offset:544
	global_atomic_add v145, v0, s[4:5] offset:608
	global_atomic_add v145, v0, s[4:5] offset:672
	global_atomic_add v145, v0, s[4:5] offset:736
	global_atomic_add v145, v0, s[4:5] offset:800
	global_atomic_add v145, v0, s[4:5] offset:864
	global_atomic_add v145, v0, s[4:5] offset:928
	global_atomic_add v145, v0, s[4:5] offset:992
	s_branch .Lgb_acq
.Lgb_poll:
	global_load_dword v1, v2, s[4:5] offset:544 sc1
	s_waitcnt vmcnt(0)
	v_cmp_le_u32_e32 vcc, s12, v1
	s_cbranch_vccnz .Lgb_acq
.Lgb_spin:
	s_sleep 8
	global_load_dword v1, v2, s[4:5] offset:544 sc1
	s_waitcnt vmcnt(0)
	v_cmp_gt_u32_e32 vcc, s12, v1
	s_cbranch_vccnz .Lgb_spin
